# stack + relaxed first-iteration vmcnt waits after each epilogue
# baseline (speedup 1.0000x reference)
	.amdhsa_kernel _Z10hybrid_fwd4Args
		.amdhsa_group_segment_fixed_size 0
		.amdhsa_private_segment_fixed_size 0
		.amdhsa_kernarg_size 368
		.amdhsa_user_sgpr_count 2
		.amdhsa_user_sgpr_dispatch_ptr 0
		.amdhsa_user_sgpr_queue_ptr 0
		.amdhsa_user_sgpr_kernarg_segment_ptr 1
		.amdhsa_user_sgpr_dispatch_id 0
		.amdhsa_user_sgpr_kernarg_preload_length 0
		.amdhsa_user_sgpr_kernarg_preload_offset 0
		.amdhsa_user_sgpr_private_segment_size 0
		.amdhsa_uses_dynamic_stack 0
		.amdhsa_enable_private_segment 0
		.amdhsa_system_sgpr_workgroup_id_x 1
		.amdhsa_system_sgpr_workgroup_id_y 0
		.amdhsa_system_sgpr_workgroup_id_z 0
		.amdhsa_system_sgpr_workgroup_info 0
		.amdhsa_system_vgpr_workitem_id 2
		.amdhsa_next_free_vgpr 256
		.amdhsa_next_free_sgpr 102
		.amdhsa_accum_offset 256
		.amdhsa_reserve_vcc 1
		.amdhsa_float_round_mode_32 0
		.amdhsa_float_round_mode_16_64 0
		.amdhsa_float_denorm_mode_32 3
		.amdhsa_float_denorm_mode_16_64 3
		.amdhsa_dx10_clamp 1
		.amdhsa_ieee_mode 1
		.amdhsa_fp16_overflow 0
		.amdhsa_tg_split 0
		.amdhsa_exception_fp_ieee_invalid_op 0
		.amdhsa_exception_fp_denorm_src 0
		.amdhsa_exception_fp_ieee_div_zero 0
		.amdhsa_exception_fp_ieee_overflow 0
		.amdhsa_exception_fp_ieee_underflow 0
		.amdhsa_exception_fp_ieee_inexact 0
		.amdhsa_exception_int_div_zero 0
	.end_amdhsa_kernel

amdhsa.kernels:
  - .agpr_count:     0
    .args:
      - .offset:         0
        .size:           112
        .value_kind:     by_value
      - .offset:         112
        .size:           4
        .value_kind:     hidden_block_count_x
      - .offset:         116
        .size:           4
        .value_kind:     hidden_block_count_y
      - .offset:         120
        .size:           4
        .value_kind:     hidden_block_count_z
      - .offset:         124
        .size:           2
        .value_kind:     hidden_group_size_x
      - .offset:         126
        .size:           2
        .value_kind:     hidden_group_size_y
      - .offset:         128
        .size:           2
        .value_kind:     hidden_group_size_z
      - .offset:         130
        .size:           2
        .value_kind:     hidden_remainder_x
      - .offset:         132
        .size:           2
        .value_kind:     hidden_remainder_y
      - .offset:         134
        .size:           2
        .value_kind:     hidden_remainder_z
      - .offset:         152
        .size:           8
        .value_kind:     hidden_global_offset_x
      - .offset:         160
        .size:           8
        .value_kind:     hidden_global_offset_y
      - .offset:         168
        .size:           8
        .value_kind:     hidden_global_offset_z
      - .offset:         176
        .size:           2
        .value_kind:     hidden_grid_dims
      - .offset:         200
        .size:           8
        .value_kind:     hidden_multigrid_sync_arg
      - .offset:         232
        .size:           4
        .value_kind:     hidden_dynamic_lds_size
    .group_segment_fixed_size: 0
    .kernarg_segment_align: 8
    .kernarg_segment_size: 368
    .language:       OpenCL C
    .language_version:
      - 2
      - 0
    .max_flat_workgroup_size: 512
    .name:           _Z10hybrid_fwd4Args
    .private_segment_fixed_size: 0
    .sgpr_count:     108
    .sgpr_spill_count: 196
    .symbol:         _Z10hybrid_fwd4Args.kd
    .uniform_work_group_size: 1
    .uses_dynamic_stack: false
    .vgpr_count:     256
    .vgpr_spill_count: 0
    .wavefront_size: 64
